# attention output: v_permlane32_swap pairs widen the 16 row-per-lane dwordx2 stores into 8 dwordx4 stores
# speedup vs baseline: 1.0165x; 1.0083x over previous
.LBB0_527:
	s_mov_b32 s100, 0x1000
	s_mov_b32 s101, 0
	v_lshl_add_u64 v[160:161], s[100:101], 0, v[136:137]
	v_lshl_add_u64 v[162:163], s[100:101], 1, v[136:137]
	v_lshl_add_u64 v[164:165], s[100:101], 0, v[162:163]
	global_load_dwordx4 v[98:101], v[136:137], off offset:3072
	global_load_dwordx4 v[94:97], v[136:137], off offset:2048
	global_load_dwordx4 v[82:85], v[136:137], off offset:1024
	global_load_dwordx4 v[70:73], v[136:137], off
	global_load_dwordx4 v[118:121], v[160:161], off offset:3072
	global_load_dwordx4 v[110:113], v[160:161], off offset:2048
	global_load_dwordx4 v[106:109], v[160:161], off offset:1024
	global_load_dwordx4 v[102:105], v[160:161], off
	global_load_dwordx4 v[114:117], v[162:163], off offset:3072
	global_load_dwordx4 v[122:125], v[162:163], off offset:2048
	global_load_dwordx4 v[130:133], v[162:163], off offset:1024
	global_load_dwordx4 v[126:129], v[162:163], off
	global_load_dwordx4 v[78:81], v[164:165], off offset:2048
	global_load_dwordx4 v[86:89], v[164:165], off offset:1024
	global_load_dwordx4 v[90:93], v[164:165], off
	global_load_dwordx4 v[74:77], v[164:165], off offset:3072
	v_mul_f32_e32 v152, s19, v0
	global_load_dwordx4 v[66:69], v[148:149], off
	s_waitcnt vmcnt(0)
	v_pk_fma_f32 v[168:169], v[62:63], v[152:153], v[98:99] op_sel_hi:[1,0,1] neg_lo:[1,0,0] neg_hi:[1,0,0]
	v_pk_fma_f32 v[164:165], v[58:59], v[152:153], v[94:95] op_sel_hi:[1,0,1] neg_lo:[1,0,0] neg_hi:[1,0,0]
	v_pk_fma_f32 v[160:161], v[54:55], v[152:153], v[82:83] op_sel_hi:[1,0,1] neg_lo:[1,0,0] neg_hi:[1,0,0]
	v_pk_fma_f32 v[156:157], v[50:51], v[152:153], v[70:71] op_sel_hi:[1,0,1] neg_lo:[1,0,0] neg_hi:[1,0,0]
	v_pk_fma_f32 v[154:155], v[52:53], v[152:153], v[72:73] op_sel_hi:[1,0,1] neg_lo:[1,0,0] neg_hi:[1,0,0]
	v_mul_f32_e32 v70, v157, v157
	v_pk_fma_f32 v[70:71], v[156:157], v[156:157], v[70:71] op_sel_hi:[1,1,0]
	v_mul_f32_e32 v72, v155, v155
	v_pk_fma_f32 v[70:71], v[154:155], v[154:155], v[70:71]
	v_pk_fma_f32 v[158:159], v[56:57], v[152:153], v[84:85] op_sel_hi:[1,0,1] neg_lo:[1,0,0] neg_hi:[1,0,0]
	v_pk_add_f32 v[162:163], v[72:73], v[70:71] op_sel_hi:[0,1]
	v_pk_fma_f32 v[82:83], v[160:161], v[160:161], v[162:163]
	v_mul_f32_e32 v84, v161, v161
	v_pk_add_f32 v[82:83], v[84:85], v[82:83] op_sel_hi:[0,1]
	v_pk_fma_f32 v[82:83], v[158:159], v[158:159], v[82:83]
	v_mul_f32_e32 v84, v159, v159
	v_pk_add_f32 v[166:167], v[84:85], v[82:83] op_sel_hi:[0,1]
	v_pk_fma_f32 v[162:163], v[60:61], v[152:153], v[96:97] op_sel_hi:[1,0,1] neg_lo:[1,0,0] neg_hi:[1,0,0]
	v_pk_fma_f32 v[94:95], v[164:165], v[164:165], v[166:167]
	v_mul_f32_e32 v96, v165, v165
	v_pk_add_f32 v[94:95], v[96:97], v[94:95] op_sel_hi:[0,1]
	v_pk_fma_f32 v[94:95], v[162:163], v[162:163], v[94:95]
	v_mul_f32_e32 v96, v163, v163
	v_pk_add_f32 v[170:171], v[96:97], v[94:95] op_sel_hi:[0,1]
	v_pk_fma_f32 v[166:167], v[64:65], v[152:153], v[100:101] op_sel_hi:[1,0,1] neg_lo:[1,0,0] neg_hi:[1,0,0]
	v_pk_fma_f32 v[98:99], v[168:169], v[168:169], v[170:171]
	v_mul_f32_e32 v100, v169, v169
	v_pk_add_f32 v[98:99], v[100:101], v[98:99] op_sel_hi:[0,1]
	v_pk_fma_f32 v[98:99], v[166:167], v[166:167], v[98:99]
	v_mul_f32_e32 v100, v167, v167
	v_pk_add_f32 v[174:175], v[100:101], v[98:99] op_sel_hi:[0,1]
	v_pk_fma_f32 v[172:173], v[34:35], v[152:153], v[102:103] op_sel_hi:[1,0,1] neg_lo:[1,0,0] neg_hi:[1,0,0]
	v_pk_fma_f32 v[170:171], v[36:37], v[152:153], v[104:105] op_sel_hi:[1,0,1] neg_lo:[1,0,0] neg_hi:[1,0,0]
	v_pk_fma_f32 v[102:103], v[172:173], v[172:173], v[174:175]
	v_mul_f32_e32 v104, v173, v173
	v_pk_add_f32 v[102:103], v[104:105], v[102:103] op_sel_hi:[0,1]
	v_pk_fma_f32 v[102:103], v[170:171], v[170:171], v[102:103]
	v_mul_f32_e32 v104, v171, v171
	v_pk_add_f32 v[178:179], v[104:105], v[102:103] op_sel_hi:[0,1]
	v_pk_fma_f32 v[176:177], v[38:39], v[152:153], v[106:107] op_sel_hi:[1,0,1] neg_lo:[1,0,0] neg_hi:[1,0,0]
	global_load_dwordx4 v[70:73], v[148:149], off offset:32
	v_pk_fma_f32 v[174:175], v[40:41], v[152:153], v[108:109] op_sel_hi:[1,0,1] neg_lo:[1,0,0] neg_hi:[1,0,0]
	v_pk_fma_f32 v[106:107], v[176:177], v[176:177], v[178:179]
	v_mul_f32_e32 v108, v177, v177
	v_pk_add_f32 v[106:107], v[108:109], v[106:107] op_sel_hi:[0,1]
	v_pk_fma_f32 v[106:107], v[174:175], v[174:175], v[106:107]
	v_mul_f32_e32 v108, v175, v175
	global_load_dwordx4 v[82:85], v[148:149], off offset:64
	global_load_dwordx4 v[94:97], v[148:149], off offset:96
	v_pk_add_f32 v[182:183], v[108:109], v[106:107] op_sel_hi:[0,1]
	v_pk_fma_f32 v[180:181], v[42:43], v[152:153], v[110:111] op_sel_hi:[1,0,1] neg_lo:[1,0,0] neg_hi:[1,0,0]
	v_pk_fma_f32 v[178:179], v[44:45], v[152:153], v[112:113] op_sel_hi:[1,0,1] neg_lo:[1,0,0] neg_hi:[1,0,0]
	v_pk_fma_f32 v[110:111], v[180:181], v[180:181], v[182:183]
	v_mul_f32_e32 v112, v181, v181
	v_pk_add_f32 v[110:111], v[112:113], v[110:111] op_sel_hi:[0,1]
	v_pk_fma_f32 v[110:111], v[178:179], v[178:179], v[110:111]
	v_mul_f32_e32 v112, v179, v179
	v_pk_add_f32 v[186:187], v[112:113], v[110:111] op_sel_hi:[0,1]
	v_pk_fma_f32 v[184:185], v[46:47], v[152:153], v[118:119] op_sel_hi:[1,0,1] neg_lo:[1,0,0] neg_hi:[1,0,0]
	v_pk_fma_f32 v[182:183], v[48:49], v[152:153], v[120:121] op_sel_hi:[1,0,1] neg_lo:[1,0,0] neg_hi:[1,0,0]
	v_pk_fma_f32 v[118:119], v[184:185], v[184:185], v[186:187]
	v_mul_f32_e32 v120, v185, v185
	global_load_dwordx4 v[98:101], v[148:149], off offset:128
	global_load_dwordx4 v[102:105], v[148:149], off offset:160
	v_pk_add_f32 v[118:119], v[120:121], v[118:119] op_sel_hi:[0,1]
	v_pk_fma_f32 v[118:119], v[182:183], v[182:183], v[118:119]
	v_mul_f32_e32 v120, v183, v183
	v_pk_add_f32 v[190:191], v[120:121], v[118:119] op_sel_hi:[0,1]
	v_pk_fma_f32 v[188:189], v[18:19], v[152:153], v[126:127] op_sel_hi:[1,0,1] neg_lo:[1,0,0] neg_hi:[1,0,0]
	v_pk_fma_f32 v[186:187], v[20:21], v[152:153], v[128:129] op_sel_hi:[1,0,1] neg_lo:[1,0,0] neg_hi:[1,0,0]
	v_pk_fma_f32 v[126:127], v[188:189], v[188:189], v[190:191]
	v_mul_f32_e32 v128, v189, v189
	v_pk_add_f32 v[126:127], v[128:129], v[126:127] op_sel_hi:[0,1]
	v_pk_fma_f32 v[126:127], v[186:187], v[186:187], v[126:127]
	v_mul_f32_e32 v128, v187, v187
	global_load_dwordx4 v[106:109], v[148:149], off offset:192
	global_load_dwordx4 v[110:113], v[148:149], off offset:224
	v_pk_add_f32 v[194:195], v[128:129], v[126:127] op_sel_hi:[0,1]
	v_pk_fma_f32 v[192:193], v[22:23], v[152:153], v[130:131] op_sel_hi:[1,0,1] neg_lo:[1,0,0] neg_hi:[1,0,0]
	v_pk_fma_f32 v[190:191], v[24:25], v[152:153], v[132:133] op_sel_hi:[1,0,1] neg_lo:[1,0,0] neg_hi:[1,0,0]
	v_pk_fma_f32 v[130:131], v[192:193], v[192:193], v[194:195]
	v_mul_f32_e32 v132, v193, v193
	v_pk_add_f32 v[130:131], v[132:133], v[130:131] op_sel_hi:[0,1]
	v_pk_fma_f32 v[130:131], v[190:191], v[190:191], v[130:131]
	v_mul_f32_e32 v132, v191, v191
	v_pk_add_f32 v[198:199], v[132:133], v[130:131] op_sel_hi:[0,1]
	v_pk_fma_f32 v[196:197], v[26:27], v[152:153], v[122:123] op_sel_hi:[1,0,1] neg_lo:[1,0,0] neg_hi:[1,0,0]
	v_pk_fma_f32 v[194:195], v[28:29], v[152:153], v[124:125] op_sel_hi:[1,0,1] neg_lo:[1,0,0] neg_hi:[1,0,0]
	v_pk_fma_f32 v[122:123], v[196:197], v[196:197], v[198:199]
	v_mul_f32_e32 v124, v197, v197
	global_load_dwordx4 v[118:121], v[148:149], off offset:256
	global_load_dwordx4 v[126:129], v[148:149], off offset:288
	v_pk_add_f32 v[122:123], v[124:125], v[122:123] op_sel_hi:[0,1]
	v_pk_fma_f32 v[122:123], v[194:195], v[194:195], v[122:123]
	v_mul_f32_e32 v124, v195, v195
	v_pk_add_f32 v[202:203], v[124:125], v[122:123] op_sel_hi:[0,1]
	v_pk_fma_f32 v[200:201], v[30:31], v[152:153], v[114:115] op_sel_hi:[1,0,1] neg_lo:[1,0,0] neg_hi:[1,0,0]
	v_pk_fma_f32 v[198:199], v[32:33], v[152:153], v[116:117] op_sel_hi:[1,0,1] neg_lo:[1,0,0] neg_hi:[1,0,0]
	v_pk_fma_f32 v[114:115], v[200:201], v[200:201], v[202:203]
	v_mul_f32_e32 v116, v201, v201
	v_pk_add_f32 v[114:115], v[116:117], v[114:115] op_sel_hi:[0,1]
	v_pk_fma_f32 v[114:115], v[198:199], v[198:199], v[114:115]
	v_mul_f32_e32 v116, v199, v199
	global_load_dwordx4 v[130:133], v[148:149], off offset:320
	global_load_dwordx4 v[122:125], v[148:149], off offset:352
	v_pk_add_f32 v[220:221], v[116:117], v[114:115] op_sel_hi:[0,1]
	v_pk_fma_f32 v[222:223], v[2:3], v[152:153], v[90:91] op_sel_hi:[1,0,1] neg_lo:[1,0,0] neg_hi:[1,0,0]
	v_pk_fma_f32 v[202:203], v[4:5], v[152:153], v[92:93] op_sel_hi:[1,0,1] neg_lo:[1,0,0] neg_hi:[1,0,0]
	v_pk_fma_f32 v[90:91], v[222:223], v[222:223], v[220:221]
	v_mul_f32_e32 v92, v223, v223
	v_pk_add_f32 v[90:91], v[92:93], v[90:91] op_sel_hi:[0,1]
	v_pk_fma_f32 v[90:91], v[202:203], v[202:203], v[90:91]
	v_mul_f32_e32 v92, v203, v203
	v_pk_add_f32 v[220:221], v[92:93], v[90:91] op_sel_hi:[0,1]
	v_pk_fma_f32 v[226:227], v[6:7], v[152:153], v[86:87] op_sel_hi:[1,0,1] neg_lo:[1,0,0] neg_hi:[1,0,0]
	v_pk_fma_f32 v[224:225], v[8:9], v[152:153], v[88:89] op_sel_hi:[1,0,1] neg_lo:[1,0,0] neg_hi:[1,0,0]
	v_pk_fma_f32 v[86:87], v[226:227], v[226:227], v[220:221]
	v_mul_f32_e32 v88, v227, v227
	global_load_dwordx4 v[114:117], v[148:149], off offset:384
	global_load_dwordx4 v[90:93], v[148:149], off offset:416
	v_pk_add_f32 v[86:87], v[88:89], v[86:87] op_sel_hi:[0,1]
	v_pk_fma_f32 v[86:87], v[224:225], v[224:225], v[86:87]
	v_mul_f32_e32 v88, v225, v225
	v_pk_add_f32 v[220:221], v[88:89], v[86:87] op_sel_hi:[0,1]
	v_pk_fma_f32 v[230:231], v[10:11], v[152:153], v[78:79] op_sel_hi:[1,0,1] neg_lo:[1,0,0] neg_hi:[1,0,0]
	v_pk_fma_f32 v[228:229], v[12:13], v[152:153], v[80:81] op_sel_hi:[1,0,1] neg_lo:[1,0,0] neg_hi:[1,0,0]
	v_pk_fma_f32 v[78:79], v[230:231], v[230:231], v[220:221]
	v_mul_f32_e32 v80, v231, v231
	v_pk_add_f32 v[78:79], v[80:81], v[78:79] op_sel_hi:[0,1]
	v_pk_fma_f32 v[78:79], v[228:229], v[228:229], v[78:79]
	v_mul_f32_e32 v80, v229, v229
	global_load_dwordx4 v[86:89], v[148:149], off offset:448
	v_pk_add_f32 v[220:221], v[80:81], v[78:79] op_sel_hi:[0,1]
	v_pk_fma_f32 v[74:75], v[14:15], v[152:153], v[74:75] op_sel_hi:[1,0,1] neg_lo:[1,0,0] neg_hi:[1,0,0]
	v_pk_fma_f32 v[76:77], v[16:17], v[152:153], v[76:77] op_sel_hi:[1,0,1] neg_lo:[1,0,0] neg_hi:[1,0,0]
	v_pk_fma_f32 v[152:153], v[74:75], v[74:75], v[220:221]
	v_mul_f32_e32 v220, v75, v75
	v_pk_add_f32 v[152:153], v[220:221], v[152:153] op_sel_hi:[0,1]
	global_load_dwordx4 v[78:81], v[148:149], off offset:480
	v_pk_fma_f32 v[152:153], v[76:77], v[76:77], v[152:153]
	v_mul_f32_e32 v220, v77, v77
	v_pk_add_f32 v[152:153], v[220:221], v[152:153] op_sel_hi:[0,1]
	v_mov_b32_e32 v153, v152
	s_nop 1
	v_permlane32_swap_b32_e32 v152, v153
	v_add_f32_e32 v152, v152, v153
	v_fmamk_f32 v152, v152, 0x3c000000, v240
	v_cmp_gt_f32_e32 vcc, s31, v152
	v_mul_f32_e32 v153, 0x4f800000, v152
	s_nop 0
	v_cndmask_b32_e32 v152, v152, v153, vcc
	v_sqrt_f32_e32 v153, v152
	s_nop 0
	v_add_u32_e32 v219, -1, v153
	v_fma_f32 v220, -v219, v153, v152
	v_cmp_ge_f32_e64 s[44:45], 0, v220
	v_add_u32_e32 v220, 1, v153
	s_nop 0
	v_cndmask_b32_e64 v219, v153, v219, s[44:45]
	v_fma_f32 v153, -v220, v153, v152
	v_cmp_lt_f32_e64 s[44:45], 0, v153
	s_nop 1
	v_cndmask_b32_e64 v153, v219, v220, s[44:45]
	v_mul_f32_e32 v219, 0x37800000, v153
	v_cndmask_b32_e32 v153, v153, v219, vcc
	v_cmp_class_f32_e32 vcc, v152, v241
	s_nop 1
	v_cndmask_b32_e32 v152, v153, v152, vcc
	v_div_scale_f32 v153, s[24:25], v152, v152, v204
	v_rcp_f32_e32 v219, v153
	s_nop 0
	v_fma_f32 v220, -v153, v219, 1.0
	v_fmac_f32_e32 v219, v220, v219
	v_div_scale_f32 v220, vcc, v204, v152, v204
	v_mul_f32_e32 v221, v220, v219
	v_fma_f32 v232, -v153, v221, v220
	v_fmac_f32_e32 v221, v232, v219
	v_fma_f32 v153, -v153, v221, v220
	v_div_fmas_f32 v153, v153, v219, v221
	v_div_fixup_f32 v152, v153, v152, v204
	v_pk_mul_f32 v[156:157], v[156:157], v[152:153] op_sel_hi:[1,0]
	v_pk_mul_f32 v[154:155], v[154:155], v[152:153] op_sel_hi:[1,0]
	v_pk_mul_f32 v[66:67], v[66:67], v[156:157]
	v_pk_mul_f32 v[68:69], v[68:69], v[154:155]
	v_cvt_pk_bf16_f32 v66, v66, v67
	v_cvt_pk_bf16_f32 v67, v68, v69
	v_mbcnt_lo_u32_b32 v248, -1, 0
	v_mbcnt_hi_u32_b32 v248, -1, v248
	v_lshrrev_b32_e32 v248, 5, v248
	v_lshlrev_b32_e32 v248, 3, v248
	v_mov_b32_e32 v249, 0
	v_lshl_add_u64 v[246:247], v[150:151], 0, v[248:249]
	v_pk_mul_f32 v[242:243], v[160:161], v[152:153] op_sel_hi:[1,0]
	v_pk_mul_f32 v[244:245], v[158:159], v[152:153] op_sel_hi:[1,0]
	s_waitcnt vmcnt(0)
	v_pk_mul_f32 v[242:243], v[70:71], v[242:243]
	v_pk_mul_f32 v[244:245], v[72:73], v[244:245]
	v_cvt_pk_bf16_f32 v68, v242, v243
	v_cvt_pk_bf16_f32 v69, v244, v245
	s_nop 1
	v_permlane32_swap_b32_e32 v66, v68
	v_permlane32_swap_b32_e32 v67, v69
	global_store_dwordx4 v[246:247], v[66:69], off
	s_nop 1
	v_pk_mul_f32 v[66:67], v[164:165], v[152:153] op_sel_hi:[1,0]
	v_pk_mul_f32 v[68:69], v[162:163], v[152:153] op_sel_hi:[1,0]
	v_pk_mul_f32 v[66:67], v[82:83], v[66:67]
	v_pk_mul_f32 v[68:69], v[84:85], v[68:69]
	v_cvt_pk_bf16_f32 v66, v66, v67
	v_cvt_pk_bf16_f32 v67, v68, v69
	v_pk_mul_f32 v[242:243], v[168:169], v[152:153] op_sel_hi:[1,0]
	v_pk_mul_f32 v[244:245], v[166:167], v[152:153] op_sel_hi:[1,0]
	v_pk_mul_f32 v[242:243], v[94:95], v[242:243]
	v_pk_mul_f32 v[244:245], v[96:97], v[244:245]
	v_cvt_pk_bf16_f32 v68, v242, v243
	v_cvt_pk_bf16_f32 v69, v244, v245
	s_nop 1
	v_permlane32_swap_b32_e32 v66, v68
	v_permlane32_swap_b32_e32 v67, v69
	global_store_dwordx4 v[246:247], v[66:69], off offset:32
	s_nop 1
	v_pk_mul_f32 v[66:67], v[172:173], v[152:153] op_sel_hi:[1,0]
	v_pk_mul_f32 v[68:69], v[170:171], v[152:153] op_sel_hi:[1,0]
	v_pk_mul_f32 v[66:67], v[66:67], v[98:99]
	v_pk_mul_f32 v[68:69], v[68:69], v[100:101]
	v_cvt_pk_bf16_f32 v66, v66, v67
	v_cvt_pk_bf16_f32 v67, v68, v69
	v_pk_mul_f32 v[242:243], v[176:177], v[152:153] op_sel_hi:[1,0]
	v_pk_mul_f32 v[244:245], v[174:175], v[152:153] op_sel_hi:[1,0]
	v_pk_mul_f32 v[242:243], v[242:243], v[102:103]
	v_pk_mul_f32 v[244:245], v[244:245], v[104:105]
	v_cvt_pk_bf16_f32 v68, v242, v243
	v_cvt_pk_bf16_f32 v69, v244, v245
	s_nop 1
	v_permlane32_swap_b32_e32 v66, v68
	v_permlane32_swap_b32_e32 v67, v69
	global_store_dwordx4 v[246:247], v[66:69], off offset:64
	s_nop 1
	v_pk_mul_f32 v[66:67], v[180:181], v[152:153] op_sel_hi:[1,0]
	v_pk_mul_f32 v[68:69], v[178:179], v[152:153] op_sel_hi:[1,0]
	v_pk_mul_f32 v[66:67], v[66:67], v[106:107]
	v_pk_mul_f32 v[68:69], v[68:69], v[108:109]
	v_cvt_pk_bf16_f32 v66, v66, v67
	v_cvt_pk_bf16_f32 v67, v68, v69
	v_pk_mul_f32 v[242:243], v[184:185], v[152:153] op_sel_hi:[1,0]
	v_pk_mul_f32 v[244:245], v[182:183], v[152:153] op_sel_hi:[1,0]
	v_pk_mul_f32 v[242:243], v[242:243], v[110:111]
	v_pk_mul_f32 v[244:245], v[244:245], v[112:113]
	v_cvt_pk_bf16_f32 v68, v242, v243
	v_cvt_pk_bf16_f32 v69, v244, v245
	s_nop 1
	v_permlane32_swap_b32_e32 v66, v68
	v_permlane32_swap_b32_e32 v67, v69
	global_store_dwordx4 v[246:247], v[66:69], off offset:96
	s_nop 1
	v_pk_mul_f32 v[66:67], v[188:189], v[152:153] op_sel_hi:[1,0]
	v_pk_mul_f32 v[68:69], v[186:187], v[152:153] op_sel_hi:[1,0]
	v_pk_mul_f32 v[66:67], v[66:67], v[118:119]
	v_pk_mul_f32 v[68:69], v[68:69], v[120:121]
	v_cvt_pk_bf16_f32 v66, v66, v67
	v_cvt_pk_bf16_f32 v67, v68, v69
	v_pk_mul_f32 v[242:243], v[192:193], v[152:153] op_sel_hi:[1,0]
	v_pk_mul_f32 v[244:245], v[190:191], v[152:153] op_sel_hi:[1,0]
	v_pk_mul_f32 v[242:243], v[242:243], v[126:127]
	v_pk_mul_f32 v[244:245], v[244:245], v[128:129]
	v_cvt_pk_bf16_f32 v68, v242, v243
	v_cvt_pk_bf16_f32 v69, v244, v245
	s_nop 1
	v_permlane32_swap_b32_e32 v66, v68
	v_permlane32_swap_b32_e32 v67, v69
	global_store_dwordx4 v[246:247], v[66:69], off offset:128
	s_nop 1
	v_pk_mul_f32 v[66:67], v[196:197], v[152:153] op_sel_hi:[1,0]
	v_pk_mul_f32 v[68:69], v[194:195], v[152:153] op_sel_hi:[1,0]
	v_pk_mul_f32 v[66:67], v[66:67], v[130:131]
	v_pk_mul_f32 v[68:69], v[68:69], v[132:133]
	v_cvt_pk_bf16_f32 v66, v66, v67
	v_cvt_pk_bf16_f32 v67, v68, v69
	v_pk_mul_f32 v[242:243], v[200:201], v[152:153] op_sel_hi:[1,0]
	v_pk_mul_f32 v[244:245], v[198:199], v[152:153] op_sel_hi:[1,0]
	v_pk_mul_f32 v[242:243], v[242:243], v[122:123]
	v_pk_mul_f32 v[244:245], v[244:245], v[124:125]
	v_cvt_pk_bf16_f32 v68, v242, v243
	v_cvt_pk_bf16_f32 v69, v244, v245
	s_nop 1
	v_permlane32_swap_b32_e32 v66, v68
	v_permlane32_swap_b32_e32 v67, v69
	global_store_dwordx4 v[246:247], v[66:69], off offset:160
	s_nop 1
	v_pk_mul_f32 v[66:67], v[222:223], v[152:153] op_sel_hi:[1,0]
	v_pk_mul_f32 v[68:69], v[202:203], v[152:153] op_sel_hi:[1,0]
	v_pk_mul_f32 v[66:67], v[66:67], v[114:115]
	v_pk_mul_f32 v[68:69], v[68:69], v[116:117]
	v_cvt_pk_bf16_f32 v66, v66, v67
	v_cvt_pk_bf16_f32 v67, v68, v69
	v_pk_mul_f32 v[242:243], v[226:227], v[152:153] op_sel_hi:[1,0]
	v_pk_mul_f32 v[244:245], v[224:225], v[152:153] op_sel_hi:[1,0]
	v_pk_mul_f32 v[242:243], v[242:243], v[90:91]
	v_pk_mul_f32 v[244:245], v[244:245], v[92:93]
	v_cvt_pk_bf16_f32 v68, v242, v243
	v_cvt_pk_bf16_f32 v69, v244, v245
	s_nop 1
	v_permlane32_swap_b32_e32 v66, v68
	v_permlane32_swap_b32_e32 v67, v69
	global_store_dwordx4 v[246:247], v[66:69], off offset:192
	s_nop 1
	v_pk_mul_f32 v[66:67], v[230:231], v[152:153] op_sel_hi:[1,0]
	v_pk_mul_f32 v[68:69], v[228:229], v[152:153] op_sel_hi:[1,0]
	v_pk_mul_f32 v[66:67], v[66:67], v[86:87]
	v_pk_mul_f32 v[68:69], v[68:69], v[88:89]
	v_cvt_pk_bf16_f32 v66, v66, v67
	v_cvt_pk_bf16_f32 v67, v68, v69
	v_pk_mul_f32 v[242:243], v[74:75], v[152:153] op_sel_hi:[1,0]
	v_pk_mul_f32 v[244:245], v[76:77], v[152:153] op_sel_hi:[1,0]
	v_pk_mul_f32 v[242:243], v[242:243], v[78:79]
	v_pk_mul_f32 v[244:245], v[244:245], v[80:81]
	v_cvt_pk_bf16_f32 v68, v242, v243
	v_cvt_pk_bf16_f32 v69, v244, v245
	s_nop 1
	v_permlane32_swap_b32_e32 v66, v68
	v_permlane32_swap_b32_e32 v67, v69
	global_store_dwordx4 v[246:247], v[66:69], off offset:224
	s_nop 1
	s_cbranch_execnz .LBB0_503
